# recurrence loader waves: counted vmcnt waits re-derived (no drain of fresh chunk loads in FINISH, no drain of stores and gate loads in LD_WRITE)
# speedup vs baseline: 1.0088x; 1.0088x over previous
; #define LBAR() do { asm volatile("s_waitcnt lgkmcnt(0)" ::: "memory"); __builtin_amdgcn_s_barrier(); asm volatile("" ::: "memory"); } while (0)
; #define GATE_LOAD(cc) do { _Pragma("unroll") for (int jj = 0; jj < 4; ++jj) gt[jj] = *(const v4u*)(Y + ((size_t)b * SEQL + 64 * (cc) + ((lt + 256 * jj) >> 4)) * 1024 + (size_t)h * 128 + 8 * foct); } while (0)
; __device__ __forceinline__ void hgrn_unit(LAS unsigned char* lds, int b, int h, const bf16* Q, const bf16* KK, const bf16* V, const bf16* PBUF, const float* DBUF, bf16* Y, const float* onw) {
;     ...
;         LD_ISSUE(0, lqA, lkA, lvA, lpA, ldA);
;         LD_WRITE(0, lqA, lkA, lvA, lpA, ldA); LD_ISSUE(1, lqA, lkA, lvA, lpA, ldA);
;         GATE_LOAD(0);
;         LBAR();
; #pragma unroll 1
;         for (int c = 0; c < 32; ++c) {
;             if (c > 0) { FINISH(c - 1); GATE_LOAD(c); }
;             if (c + 1 < 32) { LD_WRITE((c + 1) & 1, lqA, lkA, lvA, lpA, ldA); if (c + 2 < 32) LD_ISSUE(c + 2, lqA, lkA, lvA, lpA, ldA); }
;             LBAR();
.LBB0_1292:
	s_or_b64 exec, exec, s[10:11]
	s_and_b32 s8, s12, 7
	s_lshl_b32 s10, s8, 5
	s_lshl_b32 s11, s8, 8
	s_lshl_b32 s26, s18, 1
	s_add_u32 s8, s50, s26
	s_addc_u32 s9, s51, 0
	v_lshlrev_b32_e32 v116, 1, v96
	v_mov_b32_e32 v117, v0
	v_lshl_add_u64 v[94:95], s[8:9], 0, v[116:117]
	v_lshl_add_u64 v[10:11], v[94:95], 0, v[82:83]
	v_lshl_add_u64 v[12:13], v[94:95], 0, v[84:85]
	global_load_dwordx4 v[82:85], v[10:11], off
	global_load_dwordx4 v[66:69], v[12:13], off
	v_lshl_add_u64 v[10:11], v[94:95], 0, v[110:111]
	v_lshl_add_u64 v[12:13], v[94:95], 0, v[112:113]
	global_load_dwordx4 v[14:17], v[10:11], off
	s_nop 0
	global_load_dwordx4 v[10:13], v[12:13], off
	v_readlane_b32 s8, v254, 62
	v_lshl_add_u64 v[110:111], s[50:51], 0, v[116:117]
	s_lshl_b64 s[6:7], s[6:7], 22
	v_add_u32_e32 v135, s8, v116
	v_readlane_b32 s8, v252, 39
	v_readlane_b32 s9, v252, 40
	v_or_b32_e32 v147, s11, v116
	v_lshlrev_b64 v[116:117], 11, v[88:89]
	v_lshl_add_u64 v[112:113], v[114:115], 2, s[8:9]
	v_lshlrev_b64 v[114:115], 11, v[86:87]
	v_lshlrev_b64 v[118:119], 11, v[90:91]
	v_lshlrev_b64 v[120:121], 11, v[92:93]
	v_lshl_add_u64 v[122:123], s[6:7], 0, v[114:115]
	v_lshl_add_u64 v[124:125], s[6:7], 0, v[116:117]
	v_lshl_add_u64 v[126:127], s[6:7], 0, v[118:119]
	v_lshl_add_u64 v[128:129], s[6:7], 0, v[120:121]
	v_or_b32_e32 v114, v122, v147
	v_or_b32_e32 v116, v124, v147
	v_or_b32_e32 v118, v126, v147
	v_or_b32_e32 v120, v128, v147
	v_lshlrev_b32_e32 v147, 4, v1
	s_waitcnt lgkmcnt(0)
	s_barrier
	v_and_b32_e32 v147, 0xf0, v147
	s_movk_i32 s8, 0x110
	s_add_i32 s15, s15, s10
	v_mov_b32_e32 v115, v123
	v_mov_b32_e32 v117, v125
	v_mov_b32_e32 v119, v127
	v_mov_b32_e32 v121, v129
	v_or3_b32 v122, v122, s11, v147
	v_or3_b32 v124, v124, s11, v147
	v_or3_b32 v126, v126, s11, v147
	v_or3_b32 v128, v128, s11, v147
	v_lshl_add_u64 v[110:111], v[110:111], 0, s[26:27]
	v_lshlrev_b32_e32 v137, 4, v97
	v_lshlrev_b32_e32 v136, 5, v92
	v_mul_lo_u32 v134, v92, s8
	v_lshlrev_b32_e32 v133, 5, v90
	v_mul_lo_u32 v132, v90, s8
	v_lshlrev_b32_e32 v107, 5, v88
	v_mul_lo_u32 v105, v88, s8
	v_lshlrev_b32_e32 v103, 5, v86
	v_mul_lo_u32 v97, v86, s8
	s_add_i32 s15, s15, 2
	v_lshl_add_u64 v[114:115], s[82:83], 0, v[114:115]
	v_lshl_add_u64 v[116:117], s[82:83], 0, v[116:117]
	v_lshl_add_u64 v[118:119], s[82:83], 0, v[118:119]
	v_lshl_add_u64 v[120:121], s[82:83], 0, v[120:121]
	v_lshl_add_u64 v[122:123], s[50:51], 0, v[122:123]
	v_lshl_add_u64 v[124:125], s[50:51], 0, v[124:125]
	v_lshl_add_u64 v[126:127], s[50:51], 0, v[126:127]
	v_lshl_add_u64 v[128:129], s[50:51], 0, v[128:129]
	s_mov_b32 s10, 0
	s_mov_b64 s[6:7], 0
	s_movk_i32 s18, 0xffc0
	s_mov_b32 s20, s85
	s_mov_b32 s21, 0x100000
	s_waitcnt vmcnt(4)
	s_cmp_eq_u32 s6, 0
	s_cbranch_scc1 .LBB0_1294
.LBB0_1293:
	s_add_i32 s8, s10, -1
	s_and_b32 s8, s8, 1
	s_lshl_b32 s9, s8, 11
	s_add_i32 s11, s9, 0
	s_add_i32 s11, s11, 0x1e400
	v_add_u32_e32 v147, s11, v136
	ds_read_b128 v[150:153], v147
	ds_read_b128 v[154:157], v147 offset:16
	s_mulk_i32 s8, 0x4400
	v_add_u32_e32 v147, s8, v135
	v_add_u32_e32 v177, s11, v133
	s_waitcnt lgkmcnt(1)
	v_mov_b32_e32 v158, v150
	s_waitcnt lgkmcnt(0)
	v_mov_b32_e32 v159, v154
	v_mov_b32_e32 v154, v151
	v_add_u32_e32 v150, v147, v134
	v_pk_add_f32 v[154:155], v[158:159], v[154:155]
	v_mov_b32_e32 v158, v152
	v_mov_b32_e32 v159, v156
	v_mov_b32_e32 v156, v153
	ds_read_b128 v[150:153], v150
	v_pk_add_f32 v[156:157], v[158:159], v[156:157]
	s_mov_b32 s22, 0x358637bd
	v_pk_add_f32 v[158:159], v[154:155], v[156:157]
	ds_read_b128 v[154:157], v177
	s_waitcnt lgkmcnt(1)
	v_lshlrev_b32_e32 v162, 16, v150
	v_and_b32_e32 v163, 0xffff0000, v150
	v_lshlrev_b32_e32 v166, 16, v151
	v_and_b32_e32 v167, 0xffff0000, v151
	v_lshlrev_b32_e32 v170, 16, v152
	v_and_b32_e32 v171, 0xffff0000, v152
	v_lshlrev_b32_e32 v174, 16, v153
	v_and_b32_e32 v175, 0xffff0000, v153
	ds_read_b128 v[150:153], v177 offset:16
	s_waitcnt lgkmcnt(1)
	v_mov_b32_e32 v178, v154
	v_mov_b32_e32 v154, v156
	s_add_u32 s8, s2, s18
	s_addc_u32 s9, s3, 0
	s_waitcnt lgkmcnt(0)
	v_mov_b32_e32 v179, v150
	v_mov_b32_e32 v150, v155
	v_mov_b32_e32 v155, v152
	v_mov_b32_e32 v152, v157
	v_pk_add_f32 v[150:151], v[178:179], v[150:151]
	v_pk_add_f32 v[152:153], v[154:155], v[152:153]
	v_mov_b64_e32 v[154:155], s[22:23]
	v_pk_add_f32 v[150:151], v[150:151], v[152:153]
	v_mov_b32_e32 v153, v158
	v_mov_b32_e32 v152, v150
	v_mov_b32_e32 v158, v151
	v_pk_add_f32 v[150:151], v[152:153], v[158:159]
	s_brev_b32 s22, 60
	v_pk_fma_f32 v[156:157], v[150:151], s[22:23], v[154:155] op_sel_hi:[1,0,0]
	s_waitcnt vmcnt(17)
	v_lshlrev_b32_e32 v164, 16, v82
	v_mul_f32_e32 v150, 0x4b800000, v157
	v_cmp_gt_f32_e32 vcc, s33, v157
	v_and_b32_e32 v165, 0xffff0000, v82
	v_lshlrev_b32_e32 v168, 16, v83
	v_cndmask_b32_e32 v150, v157, v150, vcc
	v_rsq_f32_e32 v152, v150
	v_lshl_add_u64 v[150:151], s[8:9], 0, v[92:93]
	v_lshlrev_b64 v[150:151], 11, v[150:151]
	v_lshl_add_u64 v[158:159], v[110:111], 0, v[150:151]
	v_mul_f32_e32 v150, 0x45800000, v152
	v_cndmask_b32_e32 v178, v152, v150, vcc
	v_pk_mul_f32 v[150:151], v[178:179], v[162:163] op_sel_hi:[0,1]
	v_pk_mul_f32 v[152:153], v[178:179], v[166:167] op_sel_hi:[0,1]
	v_and_b32_e32 v169, 0xffff0000, v83
	v_pk_mul_f32 v[150:151], v[6:7], v[150:151]
	v_pk_mul_f32 v[152:153], v[8:9], v[152:153]
	v_pk_mul_f32 v[150:151], v[150:151], v[164:165]
	v_pk_mul_f32 v[152:153], v[152:153], v[168:169]
	v_cvt_pk_bf16_f32 v150, v150, v151
	v_cvt_pk_bf16_f32 v151, v152, v153
	v_pk_mul_f32 v[152:153], v[178:179], v[170:171] op_sel_hi:[0,1]
	v_lshlrev_b32_e32 v172, 16, v84
	v_and_b32_e32 v173, 0xffff0000, v84
	v_pk_mul_f32 v[152:153], v[2:3], v[152:153]
	v_cmp_gt_f32_e32 vcc, s33, v156
	v_pk_mul_f32 v[152:153], v[152:153], v[172:173]
	v_add_u32_e32 v82, v147, v132
	v_cvt_pk_bf16_f32 v152, v152, v153
	v_mul_f32_e32 v153, 0x4b800000, v156
	v_cndmask_b32_e32 v153, v156, v153, vcc
	v_lshlrev_b32_e32 v176, 16, v85
	v_and_b32_e32 v177, 0xffff0000, v85
	ds_read_b128 v[82:85], v82
	v_pk_mul_f32 v[162:163], v[178:179], v[174:175] op_sel_hi:[0,1]
	v_rsq_f32_e32 v164, v153
	v_pk_mul_f32 v[162:163], v[4:5], v[162:163]
	v_add_u32_e32 v171, s11, v103
	v_pk_mul_f32 v[156:157], v[162:163], v[176:177]
	s_waitcnt vmcnt(15)
; #define GATE_LOAD(cc) do { _Pragma("unroll") for (int jj = 0; jj < 4; ++jj) gt[jj] = *(const v4u*)(Y + ((size_t)b * SEQL + 64 * (cc) + ((lt + 256 * jj) >> 4)) * 1024 + (size_t)h * 128 + 8 * foct); } while (0)
; __device__ __forceinline__ void hgrn_unit(LAS unsigned char* lds, int b, int h, const bf16* Q, const bf16* KK, const bf16* V, const bf16* PBUF, const float* DBUF, bf16* Y, const float* onw) {
;     ...
;             if (c > 0) { FINISH(c - 1); GATE_LOAD(c); }
	v_lshlrev_b32_e32 v162, 16, v15
	v_cvt_pk_bf16_f32 v153, v156, v157
	global_store_dwordx4 v[158:159], v[150:153], off
	v_lshlrev_b32_e32 v156, 16, v66
	v_and_b32_e32 v157, 0xffff0000, v66
	v_mul_f32_e32 v150, 0x45800000, v164
	v_cndmask_b32_e32 v150, v164, v150, vcc
	s_waitcnt lgkmcnt(0)
	v_lshlrev_b32_e32 v152, 16, v82
	v_and_b32_e32 v153, 0xffff0000, v82
	v_pk_mul_f32 v[152:153], v[150:151], v[152:153] op_sel_hi:[0,1]
	v_pk_mul_f32 v[152:153], v[6:7], v[152:153]
	v_lshlrev_b32_e32 v82, 16, v83
	v_and_b32_e32 v83, 0xffff0000, v83
	v_pk_mul_f32 v[152:153], v[152:153], v[156:157]
	v_pk_mul_f32 v[82:83], v[150:151], v[82:83] op_sel_hi:[0,1]
	v_cvt_pk_bf16_f32 v66, v152, v153
	v_pk_mul_f32 v[82:83], v[8:9], v[82:83]
	v_lshlrev_b32_e32 v152, 16, v67
	v_and_b32_e32 v153, 0xffff0000, v67
	v_pk_mul_f32 v[82:83], v[82:83], v[152:153]
	v_lshlrev_b32_e32 v152, 16, v68
	v_cvt_pk_bf16_f32 v67, v82, v83
	v_lshlrev_b32_e32 v82, 16, v84
	v_and_b32_e32 v83, 0xffff0000, v84
	v_pk_mul_f32 v[82:83], v[150:151], v[82:83] op_sel_hi:[0,1]
	v_pk_mul_f32 v[82:83], v[2:3], v[82:83]
	v_and_b32_e32 v153, 0xffff0000, v68
	v_pk_mul_f32 v[82:83], v[82:83], v[152:153]
	v_lshlrev_b32_e32 v84, 16, v69
	v_cvt_pk_bf16_f32 v68, v82, v83
	v_lshlrev_b32_e32 v82, 16, v85
	v_and_b32_e32 v83, 0xffff0000, v85
	v_pk_mul_f32 v[82:83], v[150:151], v[82:83] op_sel_hi:[0,1]
	v_pk_mul_f32 v[82:83], v[4:5], v[82:83]
	v_and_b32_e32 v85, 0xffff0000, v69
	v_pk_mul_f32 v[82:83], v[82:83], v[84:85]
	v_add_u32_e32 v150, s11, v107
	v_cvt_pk_bf16_f32 v69, v82, v83
	ds_read_b128 v[82:85], v150
	ds_read_b128 v[150:153], v150 offset:16
	v_lshl_add_u64 v[156:157], s[8:9], 0, v[90:91]
	v_lshlrev_b64 v[156:157], 11, v[156:157]
	v_lshl_add_u64 v[156:157], v[110:111], 0, v[156:157]
	global_store_dwordx4 v[156:157], v[66:69], off
	v_lshlrev_b32_e32 v156, 16, v14
	v_and_b32_e32 v157, 0xffff0000, v14
	s_waitcnt lgkmcnt(1)
	v_mov_b32_e32 v66, v82
	s_waitcnt lgkmcnt(0)
	v_mov_b32_e32 v67, v150
	v_mov_b32_e32 v150, v83
	v_pk_add_f32 v[82:83], v[66:67], v[150:151]
	v_add_u32_e32 v66, v147, v105
	ds_read_b128 v[66:69], v66
	v_mov_b32_e32 v150, v84
	v_mov_b32_e32 v151, v152
	v_mov_b32_e32 v152, v85
	v_pk_add_f32 v[84:85], v[150:151], v[152:153]
	v_and_b32_e32 v163, 0xffff0000, v15
	v_pk_add_f32 v[150:151], v[82:83], v[84:85]
	ds_read_b128 v[82:85], v171
	s_waitcnt lgkmcnt(1)
	v_lshlrev_b32_e32 v152, 16, v66
	v_and_b32_e32 v153, 0xffff0000, v66
	v_lshlrev_b32_e32 v158, 16, v67
	v_and_b32_e32 v159, 0xffff0000, v67
	v_lshlrev_b32_e32 v164, 16, v68
	v_and_b32_e32 v165, 0xffff0000, v68
	v_lshlrev_b32_e32 v168, 16, v69
	v_and_b32_e32 v169, 0xffff0000, v69
	ds_read_b128 v[66:69], v171 offset:16
	s_waitcnt lgkmcnt(1)
	v_mov_b32_e32 v172, v82
	v_mov_b32_e32 v82, v84
	v_lshlrev_b32_e32 v166, 16, v16
	v_and_b32_e32 v167, 0xffff0000, v16
	s_waitcnt lgkmcnt(0)
	v_mov_b32_e32 v173, v66
	v_mov_b32_e32 v66, v83
	v_mov_b32_e32 v83, v68
	v_mov_b32_e32 v68, v85
	v_pk_add_f32 v[66:67], v[172:173], v[66:67]
	v_pk_add_f32 v[68:69], v[82:83], v[68:69]
	v_add_u32_e32 v14, v147, v97
	v_pk_add_f32 v[66:67], v[66:67], v[68:69]
	v_mov_b32_e32 v69, v150
	v_mov_b32_e32 v68, v66
	v_mov_b32_e32 v150, v67
	v_pk_add_f32 v[66:67], v[68:69], v[150:151]
	v_lshlrev_b32_e32 v170, 16, v17
	v_pk_fma_f32 v[82:83], v[66:67], s[22:23], v[154:155] op_sel_hi:[1,0,0]
	v_and_b32_e32 v171, 0xffff0000, v17
	v_mul_f32_e32 v66, 0x4b800000, v83
	v_cmp_gt_f32_e32 vcc, s33, v83
	ds_read_b128 v[14:17], v14
	s_nop 0
	v_cndmask_b32_e32 v66, v83, v66, vcc
	v_rsq_f32_e32 v68, v66
	v_lshl_add_u64 v[66:67], s[8:9], 0, v[88:89]
	v_lshlrev_b64 v[66:67], 11, v[66:67]
	v_lshl_add_u64 v[84:85], v[110:111], 0, v[66:67]
	v_mul_f32_e32 v66, 0x45800000, v68
	v_cndmask_b32_e32 v150, v68, v66, vcc
	v_pk_mul_f32 v[66:67], v[150:151], v[152:153] op_sel_hi:[0,1]
	v_pk_mul_f32 v[68:69], v[150:151], v[158:159] op_sel_hi:[0,1]
	v_pk_mul_f32 v[66:67], v[6:7], v[66:67]
	v_pk_mul_f32 v[68:69], v[8:9], v[68:69]
	v_pk_mul_f32 v[66:67], v[66:67], v[156:157]
	v_pk_mul_f32 v[68:69], v[68:69], v[162:163]
	v_cvt_pk_bf16_f32 v66, v66, v67
	v_cvt_pk_bf16_f32 v67, v68, v69
	v_pk_mul_f32 v[68:69], v[150:151], v[164:165] op_sel_hi:[0,1]
	v_pk_mul_f32 v[68:69], v[2:3], v[68:69]
	v_cmp_gt_f32_e32 vcc, s33, v82
	v_pk_mul_f32 v[68:69], v[68:69], v[166:167]
	v_pk_mul_f32 v[150:151], v[150:151], v[168:169] op_sel_hi:[0,1]
	v_cvt_pk_bf16_f32 v68, v68, v69
	v_mul_f32_e32 v69, 0x4b800000, v82
	v_cndmask_b32_e32 v69, v82, v69, vcc
	v_rsq_f32_e32 v147, v69
	v_pk_mul_f32 v[150:151], v[4:5], v[150:151]
	s_nop 0
	v_pk_mul_f32 v[82:83], v[150:151], v[170:171]
	s_nop 0
	v_cvt_pk_bf16_f32 v69, v82, v83
	global_store_dwordx4 v[84:85], v[66:69], off
	s_waitcnt vmcnt(17)
	v_lshlrev_b32_e32 v82, 16, v10
	v_and_b32_e32 v83, 0xffff0000, v10
	v_mul_f32_e32 v66, 0x45800000, v147
	v_cndmask_b32_e32 v66, v147, v66, vcc
	s_waitcnt lgkmcnt(0)
	v_lshlrev_b32_e32 v68, 16, v14
	v_and_b32_e32 v69, 0xffff0000, v14
	v_pk_mul_f32 v[68:69], v[66:67], v[68:69] op_sel_hi:[0,1]
	v_pk_mul_f32 v[68:69], v[6:7], v[68:69]
	v_lshlrev_b32_e32 v14, 16, v15
	v_and_b32_e32 v15, 0xffff0000, v15
	v_pk_mul_f32 v[68:69], v[68:69], v[82:83]
	v_pk_mul_f32 v[14:15], v[66:67], v[14:15] op_sel_hi:[0,1]
	v_cvt_pk_bf16_f32 v10, v68, v69
	v_pk_mul_f32 v[14:15], v[8:9], v[14:15]
	v_lshlrev_b32_e32 v68, 16, v11
	v_and_b32_e32 v69, 0xffff0000, v11
	v_pk_mul_f32 v[14:15], v[14:15], v[68:69]
	v_lshlrev_b32_e32 v68, 16, v12
	v_cvt_pk_bf16_f32 v11, v14, v15
	v_lshlrev_b32_e32 v14, 16, v16
	v_and_b32_e32 v15, 0xffff0000, v16
	v_pk_mul_f32 v[14:15], v[66:67], v[14:15] op_sel_hi:[0,1]
	v_pk_mul_f32 v[14:15], v[2:3], v[14:15]
	v_and_b32_e32 v69, 0xffff0000, v12
	v_pk_mul_f32 v[14:15], v[14:15], v[68:69]
	v_lshlrev_b32_e32 v16, 16, v13
	v_cvt_pk_bf16_f32 v12, v14, v15
	v_lshlrev_b32_e32 v14, 16, v17
	v_and_b32_e32 v15, 0xffff0000, v17
	v_pk_mul_f32 v[14:15], v[66:67], v[14:15] op_sel_hi:[0,1]
	v_pk_mul_f32 v[14:15], v[4:5], v[14:15]
	v_and_b32_e32 v17, 0xffff0000, v13
	v_pk_mul_f32 v[14:15], v[14:15], v[16:17]
	s_nop 0
	v_cvt_pk_bf16_f32 v13, v14, v15
	v_lshl_add_u64 v[14:15], s[8:9], 0, v[86:87]
	v_lshlrev_b64 v[14:15], 11, v[14:15]
	v_lshl_add_u64 v[14:15], v[110:111], 0, v[14:15]
	global_store_dwordx4 v[14:15], v[10:13], off
	s_nop 1
	v_lshl_add_u64 v[10:11], v[128:129], 0, s[6:7]
	v_lshl_add_u64 v[12:13], v[126:127], 0, s[6:7]
	global_load_dwordx4 v[82:85], v[10:11], off
	global_load_dwordx4 v[66:69], v[12:13], off
	v_lshl_add_u64 v[10:11], v[124:125], 0, s[6:7]
	v_lshl_add_u64 v[12:13], v[122:123], 0, s[6:7]
	global_load_dwordx4 v[14:17], v[10:11], off
	s_nop 0
	global_load_dwordx4 v[10:13], v[12:13], off
; __device__ __forceinline__ void hgrn_unit(LAS unsigned char* lds, int b, int h, const bf16* Q, const bf16* KK, const bf16* V, const bf16* PBUF, const float* DBUF, bf16* Y, const float* onw) {
;     ...
;             if (c + 1 < 32) { LD_WRITE((c + 1) & 1, lqA, lkA, lvA, lpA, ldA); if (c + 2 < 32) LD_ISSUE(c + 2, lqA, lkA, lvA, lpA, ldA); }
.LBB0_1294:
	s_add_i32 s19, s10, 1
	s_cmp_eq_u32 s6, 0x3e0000
	s_cbranch_scc1 .LBB0_1302
	s_bitcmp1_b32 s19, 0
	s_cselect_b32 s8, 0xf200, 0
	s_add_i32 s11, s8, 0
	v_lshl_add_u32 v147, v102, 1, s11
	s_waitcnt vmcnt(21)
	ds_write_b128 v147, v[18:21]
	s_waitcnt vmcnt(20)
	ds_write_b128 v147, v[22:25] offset:17408
	s_waitcnt vmcnt(19)
	ds_write_b128 v147, v[26:29] offset:34816
	v_lshl_add_u32 v147, v104, 1, s11
	s_waitcnt vmcnt(18)
	ds_write_b128 v147, v[30:33]
	s_waitcnt vmcnt(17)
	ds_write_b128 v147, v[34:37] offset:17408
	s_waitcnt vmcnt(16)
	ds_write_b128 v147, v[38:41] offset:34816
	v_lshl_add_u32 v147, v106, 1, s11
	s_waitcnt vmcnt(15)
	ds_write_b128 v147, v[42:45]
	s_waitcnt vmcnt(14)
	ds_write_b128 v147, v[46:49] offset:17408
	s_waitcnt vmcnt(13)
	ds_write_b128 v147, v[50:53] offset:34816
	v_lshl_add_u32 v147, v108, 1, s11
	s_waitcnt vmcnt(12)
	ds_write_b128 v147, v[54:57]
	s_waitcnt vmcnt(11)
	ds_write_b128 v147, v[58:61] offset:17408
	s_waitcnt vmcnt(10)
	ds_write_b128 v147, v[62:65] offset:34816
	v_lshl_add_u32 v147, v109, 1, s11
	v_add_u32_e32 v150, v147, v130
	v_add_u32_e32 v147, v147, v131
	s_waitcnt vmcnt(9)
	ds_write_b128 v150, v[70:73] offset:52224
	s_waitcnt vmcnt(8)
	ds_write_b128 v147, v[74:77] offset:52224
	s_and_saveexec_b64 s[8:9], s[0:1]
	v_add_u32_e32 v147, s11, v137
	ds_write_b128 v147, v[78:81] offset:61440
	s_or_b64 exec, exec, s[8:9]
	s_cmp_gt_u32 s10, 30
	s_cbranch_scc1 .LBB0_1301
	v_lshl_add_u64 v[26:27], v[120:121], 0, s[6:7]
	v_add_co_u32_e32 v18, vcc, 0x5740000, v26
	v_lshl_add_u64 v[34:35], v[118:119], 0, s[6:7]
	s_nop 0
	v_addc_co_u32_e32 v19, vcc, 0, v27, vcc
	v_add_co_u32_e32 v22, vcc, 0x7740000, v26
	s_mov_b32 s8, 0x5740000
	s_nop 0
	v_addc_co_u32_e32 v23, vcc, 0, v27, vcc
	v_add_co_u32_e32 v26, vcc, 0x9740000, v26
	v_lshl_add_u64 v[50:51], v[116:117], 0, s[6:7]
	s_nop 0
	v_addc_co_u32_e32 v27, vcc, 0, v27, vcc
	v_add_co_u32_e32 v30, vcc, s8, v34
	v_lshl_add_u64 v[58:59], v[114:115], 0, s[6:7]
	s_nop 0
	v_addc_co_u32_e32 v31, vcc, 0, v35, vcc
	v_add_co_u32_e32 v36, vcc, 0x7740000, v34
	global_load_dwordx4 v[18:21], v[18:19], off
	s_nop 0
	global_load_dwordx4 v[22:25], v[22:23], off
	v_addc_co_u32_e32 v37, vcc, 0, v35, vcc
	v_add_co_u32_e32 v38, vcc, 0x9740000, v34
	global_load_dwordx4 v[26:29], v[26:27], off
	s_nop 0
	global_load_dwordx4 v[30:33], v[30:31], off
	v_addc_co_u32_e32 v39, vcc, 0, v35, vcc
	v_add_co_u32_e32 v42, vcc, s8, v50
	global_load_dwordx4 v[34:37], v[36:37], off
	s_nop 0
	global_load_dwordx4 v[38:41], v[38:39], off
	v_addc_co_u32_e32 v43, vcc, 0, v51, vcc
	v_add_co_u32_e32 v46, vcc, 0x7740000, v50
	v_mov_b32_e32 v81, 0
	s_nop 0
	v_addc_co_u32_e32 v47, vcc, 0, v51, vcc
	v_add_co_u32_e32 v50, vcc, 0x9740000, v50
	global_load_dwordx4 v[42:45], v[42:43], off
	s_nop 0
	global_load_dwordx4 v[46:49], v[46:47], off
	v_addc_co_u32_e32 v51, vcc, 0, v51, vcc
	v_add_co_u32_e32 v54, vcc, s8, v58
	s_add_i32 s8, s15, s10
	s_nop 0
	v_addc_co_u32_e32 v55, vcc, 0, v59, vcc
	s_ashr_i32 s9, s8, 31
	v_add_co_u32_e32 v60, vcc, 0x7740000, v58
	s_lshl_b64 s[10:11], s[8:9], 13
	s_nop 0
	v_addc_co_u32_e32 v61, vcc, 0, v59, vcc
	s_add_u32 s10, s80, s10
	v_add_co_u32_e32 v62, vcc, 0x9740000, v58
	s_addc_u32 s11, s81, s11
	s_nop 0
	v_addc_co_u32_e32 v63, vcc, 0, v59, vcc
	v_lshl_add_u64 v[70:71], v[98:99], 1, s[10:11]
	v_lshl_add_u64 v[74:75], v[100:101], 1, s[10:11]
	global_load_dwordx4 v[50:53], v[50:51], off
	s_nop 0
	global_load_dwordx4 v[54:57], v[54:55], off
	s_nop 0
	global_load_dwordx4 v[58:61], v[60:61], off
	s_nop 0
	global_load_dwordx4 v[62:65], v[62:63], off
	s_nop 0
	global_load_dwordx4 v[70:73], v[70:71], off
	s_nop 0
	global_load_dwordx4 v[74:77], v[74:75], off
	v_mov_b32_e32 v80, 0
	v_mov_b32_e32 v79, 0
	v_mov_b32_e32 v78, 0
	s_and_saveexec_b64 s[10:11], s[0:1]
	s_cbranch_execz .LBB0_1300
	s_lshl_b64 s[8:9], s[8:9], 9
	v_lshl_add_u64 v[78:79], v[112:113], 0, s[8:9]
	global_load_dwordx4 v[78:81], v[78:79], off

; __device__ __forceinline__ void hgrn_unit(LAS unsigned char* lds, int b, int h, const bf16* Q, const bf16* KK, const bf16* V, const bf16* PBUF, const float* DBUF, bf16* Y, const float* onw) {
;     ...
;         FINISH(31);
.LBB0_1304:
	s_waitcnt vmcnt(8)
	v_readlane_b32 s1, v255, 0
	v_readlane_b32 s0, v254, 63
	s_or_b32 s2, s2, 0x7c0
	s_waitcnt vmcnt(12)
	v_add_u32_e32 v22, s1, v136
	ds_read_b128 v[18:21], v22
	ds_read_b128 v[22:25], v22 offset:16
	s_waitcnt vmcnt(5)
	v_lshl_add_u32 v50, v96, 1, s0
	s_mov_b32 s0, 0x358637bd
	s_waitcnt vmcnt(3)
	v_lshlrev_b32_e32 v34, 16, v82
	s_waitcnt lgkmcnt(1)
	v_mov_b32_e32 v26, v18
	s_waitcnt lgkmcnt(0)
	v_mov_b32_e32 v27, v22
	v_mov_b32_e32 v22, v19
	v_add_u32_e32 v18, v50, v134
	v_pk_add_f32 v[22:23], v[26:27], v[22:23]
	v_mov_b32_e32 v26, v20
	v_mov_b32_e32 v27, v24
	v_mov_b32_e32 v24, v21
	ds_read_b128 v[18:21], v18
	v_pk_add_f32 v[24:25], v[26:27], v[24:25]
	v_add_u32_e32 v26, s1, v133
	v_pk_add_f32 v[30:31], v[22:23], v[24:25]
	ds_read_b128 v[22:25], v26
	s_waitcnt lgkmcnt(1)
	v_lshlrev_b32_e32 v32, 16, v18
	v_and_b32_e32 v33, 0xffff0000, v18
	v_lshlrev_b32_e32 v36, 16, v19
	v_and_b32_e32 v37, 0xffff0000, v19
	v_lshlrev_b32_e32 v40, 16, v20
	v_and_b32_e32 v41, 0xffff0000, v20
	v_lshlrev_b32_e32 v44, 16, v21
	v_and_b32_e32 v45, 0xffff0000, v21
	ds_read_b128 v[18:21], v26 offset:16
	s_waitcnt lgkmcnt(1)
	v_mov_b32_e32 v48, v22
	v_add_u32_e32 v22, v50, v132
	ds_read_b128 v[26:29], v22
	v_mov_b32_e32 v22, v24
	s_waitcnt lgkmcnt(1)
	v_mov_b32_e32 v49, v18
	v_mov_b32_e32 v18, v23
	v_mov_b32_e32 v23, v20
	v_mov_b32_e32 v20, v25
	v_pk_add_f32 v[18:19], v[48:49], v[18:19]
	v_pk_add_f32 v[20:21], v[22:23], v[20:21]
	v_and_b32_e32 v35, 0xffff0000, v82
	v_pk_add_f32 v[18:19], v[18:19], v[20:21]
	v_mov_b32_e32 v21, v30
	v_mov_b32_e32 v20, v18
	v_mov_b32_e32 v30, v19
	v_pk_add_f32 v[18:19], v[20:21], v[30:31]
	v_mov_b64_e32 v[30:31], s[0:1]
	s_brev_b32 s0, 60
	v_pk_fma_f32 v[22:23], v[18:19], s[0:1], v[30:31] op_sel_hi:[1,0,0]
	v_lshlrev_b32_e32 v38, 16, v83
	v_mul_f32_e32 v18, 0x4b800000, v23
	v_cmp_gt_f32_e32 vcc, s33, v23
	v_and_b32_e32 v39, 0xffff0000, v83
	v_lshlrev_b32_e32 v42, 16, v84
	v_cndmask_b32_e32 v18, v23, v18, vcc
	v_rsq_f32_e32 v20, v18
	v_lshl_add_u64 v[18:19], s[2:3], 0, v[92:93]
	v_lshlrev_b64 v[18:19], 11, v[18:19]
	v_lshl_add_u64 v[24:25], v[94:95], 0, v[18:19]
	v_mul_f32_e32 v18, 0x45800000, v20
	v_cndmask_b32_e32 v48, v20, v18, vcc
	v_pk_mul_f32 v[18:19], v[48:49], v[32:33] op_sel_hi:[0,1]
	v_pk_mul_f32 v[20:21], v[48:49], v[36:37] op_sel_hi:[0,1]
	v_pk_mul_f32 v[18:19], v[6:7], v[18:19]
	v_pk_mul_f32 v[20:21], v[8:9], v[20:21]
	v_pk_mul_f32 v[18:19], v[18:19], v[34:35]
	v_pk_mul_f32 v[20:21], v[20:21], v[38:39]
	v_cvt_pk_bf16_f32 v18, v18, v19
	v_cvt_pk_bf16_f32 v19, v20, v21
	v_pk_mul_f32 v[20:21], v[48:49], v[40:41] op_sel_hi:[0,1]
	v_and_b32_e32 v43, 0xffff0000, v84
	v_pk_mul_f32 v[20:21], v[2:3], v[20:21]
	v_cmp_gt_f32_e32 vcc, s33, v22
	v_pk_mul_f32 v[20:21], v[20:21], v[42:43]
	v_pk_mul_f32 v[32:33], v[48:49], v[44:45] op_sel_hi:[0,1]
	v_cvt_pk_bf16_f32 v20, v20, v21
	v_mul_f32_e32 v21, 0x4b800000, v22
	v_cndmask_b32_e32 v21, v22, v21, vcc
	v_rsq_f32_e32 v34, v21
	v_lshlrev_b32_e32 v46, 16, v85
	v_and_b32_e32 v47, 0xffff0000, v85
	v_pk_mul_f32 v[32:33], v[4:5], v[32:33]
	v_add_u32_e32 v45, s1, v103
	v_pk_mul_f32 v[22:23], v[32:33], v[46:47]
	v_lshl_add_u64 v[32:33], s[2:3], 0, v[90:91]
	v_cvt_pk_bf16_f32 v21, v22, v23
	global_store_dwordx4 v[24:25], v[18:21], off
	s_waitcnt vmcnt(3)
	v_lshlrev_b32_e32 v24, 16, v67
	v_and_b32_e32 v25, 0xffff0000, v67
	v_mul_f32_e32 v18, 0x45800000, v34
	v_cndmask_b32_e32 v22, v34, v18, vcc
	s_waitcnt lgkmcnt(0)
	v_lshlrev_b32_e32 v18, 16, v26
	v_and_b32_e32 v19, 0xffff0000, v26
	v_pk_mul_f32 v[18:19], v[22:23], v[18:19] op_sel_hi:[0,1]
	v_pk_mul_f32 v[18:19], v[6:7], v[18:19]
	v_lshlrev_b32_e32 v20, 16, v66
	v_and_b32_e32 v21, 0xffff0000, v66
	v_pk_mul_f32 v[18:19], v[18:19], v[20:21]
	v_lshlrev_b32_e32 v20, 16, v27
	v_and_b32_e32 v21, 0xffff0000, v27
	v_pk_mul_f32 v[20:21], v[22:23], v[20:21] op_sel_hi:[0,1]
	v_pk_mul_f32 v[20:21], v[8:9], v[20:21]
	v_cvt_pk_bf16_f32 v18, v18, v19
	v_pk_mul_f32 v[20:21], v[20:21], v[24:25]
	v_lshlrev_b32_e32 v24, 16, v68
	v_cvt_pk_bf16_f32 v19, v20, v21
	v_lshlrev_b32_e32 v20, 16, v28
	v_and_b32_e32 v21, 0xffff0000, v28
	v_pk_mul_f32 v[20:21], v[22:23], v[20:21] op_sel_hi:[0,1]
	v_pk_mul_f32 v[20:21], v[2:3], v[20:21]
	v_and_b32_e32 v25, 0xffff0000, v68
	v_pk_mul_f32 v[20:21], v[20:21], v[24:25]
	v_lshlrev_b32_e32 v24, 16, v29
	v_and_b32_e32 v25, 0xffff0000, v29
	v_pk_mul_f32 v[22:23], v[22:23], v[24:25] op_sel_hi:[0,1]
	v_pk_mul_f32 v[22:23], v[4:5], v[22:23]
	v_lshlrev_b32_e32 v24, 16, v69
	v_and_b32_e32 v25, 0xffff0000, v69
	v_pk_mul_f32 v[22:23], v[22:23], v[24:25]
	v_add_u32_e32 v26, s1, v107
	v_cvt_pk_bf16_f32 v20, v20, v21
	v_cvt_pk_bf16_f32 v21, v22, v23
	ds_read_b128 v[22:25], v26
	ds_read_b128 v[26:29], v26 offset:16
	v_lshlrev_b64 v[32:33], 11, v[32:33]
	v_lshl_add_u64 v[32:33], v[94:95], 0, v[32:33]
	global_store_dwordx4 v[32:33], v[18:21], off
	s_waitcnt vmcnt(3)
	v_lshlrev_b32_e32 v32, 16, v14
	v_and_b32_e32 v33, 0xffff0000, v14
	s_waitcnt lgkmcnt(1)
	v_mov_b32_e32 v18, v22
	s_waitcnt lgkmcnt(0)
	v_mov_b32_e32 v19, v26
	v_mov_b32_e32 v26, v23
	v_pk_add_f32 v[22:23], v[18:19], v[26:27]
	v_add_u32_e32 v18, v50, v105
	ds_read_b128 v[18:21], v18
	v_mov_b32_e32 v26, v24
	v_mov_b32_e32 v27, v28
	v_mov_b32_e32 v28, v25
	v_pk_add_f32 v[24:25], v[26:27], v[28:29]
	v_lshlrev_b32_e32 v36, 16, v15
	v_pk_add_f32 v[26:27], v[22:23], v[24:25]
	ds_read_b128 v[22:25], v45
	s_waitcnt lgkmcnt(1)
	v_lshlrev_b32_e32 v28, 16, v18
	v_and_b32_e32 v29, 0xffff0000, v18
	v_lshlrev_b32_e32 v34, 16, v19
	v_and_b32_e32 v35, 0xffff0000, v19
	v_lshlrev_b32_e32 v38, 16, v20
	v_and_b32_e32 v39, 0xffff0000, v20
	v_lshlrev_b32_e32 v42, 16, v21
	v_and_b32_e32 v43, 0xffff0000, v21
	ds_read_b128 v[18:21], v45 offset:16
	s_waitcnt lgkmcnt(1)
	v_mov_b32_e32 v46, v22
	v_mov_b32_e32 v22, v24
	v_and_b32_e32 v37, 0xffff0000, v15
	v_lshlrev_b32_e32 v40, 16, v16
	s_waitcnt lgkmcnt(0)
	v_mov_b32_e32 v47, v18
	v_mov_b32_e32 v18, v23
	v_mov_b32_e32 v23, v20
	v_mov_b32_e32 v20, v25
	v_pk_add_f32 v[18:19], v[46:47], v[18:19]
	v_pk_add_f32 v[20:21], v[22:23], v[20:21]
	v_and_b32_e32 v41, 0xffff0000, v16
	v_pk_add_f32 v[18:19], v[18:19], v[20:21]
	v_mov_b32_e32 v21, v26
	v_mov_b32_e32 v20, v18
	v_mov_b32_e32 v26, v19
	v_pk_add_f32 v[18:19], v[20:21], v[26:27]
	v_add_u32_e32 v14, v50, v97
	v_pk_fma_f32 v[22:23], v[18:19], s[0:1], v[30:31] op_sel_hi:[1,0,0]
	v_lshlrev_b32_e32 v44, 16, v17
	v_mul_f32_e32 v18, 0x4b800000, v23
	v_cmp_gt_f32_e32 vcc, s33, v23
	v_and_b32_e32 v45, 0xffff0000, v17
	ds_read_b128 v[14:17], v14
	v_cndmask_b32_e32 v18, v23, v18, vcc
	v_rsq_f32_e32 v20, v18
	v_lshl_add_u64 v[18:19], s[2:3], 0, v[88:89]
	v_lshlrev_b64 v[18:19], 11, v[18:19]
	v_lshl_add_u64 v[24:25], v[94:95], 0, v[18:19]
	v_mul_f32_e32 v18, 0x45800000, v20
	v_cndmask_b32_e32 v26, v20, v18, vcc
	v_pk_mul_f32 v[18:19], v[26:27], v[28:29] op_sel_hi:[0,1]
	v_pk_mul_f32 v[20:21], v[26:27], v[34:35] op_sel_hi:[0,1]
	v_pk_mul_f32 v[18:19], v[6:7], v[18:19]
	v_pk_mul_f32 v[20:21], v[8:9], v[20:21]
	v_pk_mul_f32 v[18:19], v[18:19], v[32:33]
	v_pk_mul_f32 v[20:21], v[20:21], v[36:37]
	v_cvt_pk_bf16_f32 v18, v18, v19
	v_cvt_pk_bf16_f32 v19, v20, v21
	v_pk_mul_f32 v[20:21], v[26:27], v[38:39] op_sel_hi:[0,1]
	v_pk_mul_f32 v[20:21], v[2:3], v[20:21]
	v_cmp_gt_f32_e32 vcc, s33, v22
	v_pk_mul_f32 v[20:21], v[20:21], v[40:41]
	v_pk_mul_f32 v[26:27], v[26:27], v[42:43] op_sel_hi:[0,1]
	v_cvt_pk_bf16_f32 v20, v20, v21
	v_mul_f32_e32 v21, 0x4b800000, v22
	v_cndmask_b32_e32 v21, v22, v21, vcc
	v_rsq_f32_e32 v28, v21
	v_pk_mul_f32 v[26:27], v[4:5], v[26:27]
	s_mov_b64 s[0:1], 0
	v_pk_mul_f32 v[22:23], v[26:27], v[44:45]
	s_nop 0
	v_cvt_pk_bf16_f32 v21, v22, v23
	global_store_dwordx4 v[24:25], v[18:21], off
	s_nop 1
	v_mul_f32_e32 v18, 0x45800000, v28
	v_cndmask_b32_e32 v18, v28, v18, vcc
	s_waitcnt lgkmcnt(0)
	v_lshlrev_b32_e32 v20, 16, v14
	v_and_b32_e32 v21, 0xffff0000, v14
	v_lshlrev_b32_e32 v14, 16, v15
	v_and_b32_e32 v15, 0xffff0000, v15
	v_pk_mul_f32 v[20:21], v[18:19], v[20:21] op_sel_hi:[0,1]
	v_pk_mul_f32 v[14:15], v[18:19], v[14:15] op_sel_hi:[0,1]
	v_pk_mul_f32 v[6:7], v[6:7], v[20:21]
	s_waitcnt vmcnt(3)
	v_lshlrev_b32_e32 v20, 16, v10
	v_and_b32_e32 v21, 0xffff0000, v10
	v_pk_mul_f32 v[8:9], v[8:9], v[14:15]
	v_lshlrev_b32_e32 v10, 16, v11
	v_and_b32_e32 v11, 0xffff0000, v11
	v_pk_mul_f32 v[6:7], v[6:7], v[20:21]
	v_pk_mul_f32 v[8:9], v[8:9], v[10:11]
	v_cvt_pk_bf16_f32 v6, v6, v7
	v_cvt_pk_bf16_f32 v7, v8, v9
	v_lshlrev_b32_e32 v8, 16, v16
	v_and_b32_e32 v9, 0xffff0000, v16
	v_pk_mul_f32 v[8:9], v[18:19], v[8:9] op_sel_hi:[0,1]
	v_pk_mul_f32 v[2:3], v[2:3], v[8:9]
	v_lshlrev_b32_e32 v8, 16, v12
	v_and_b32_e32 v9, 0xffff0000, v12
	v_pk_mul_f32 v[2:3], v[2:3], v[8:9]
	s_nop 0
	v_cvt_pk_bf16_f32 v8, v2, v3
	v_lshlrev_b32_e32 v2, 16, v17
	v_and_b32_e32 v3, 0xffff0000, v17
	v_pk_mul_f32 v[2:3], v[18:19], v[2:3] op_sel_hi:[0,1]
	v_pk_mul_f32 v[2:3], v[4:5], v[2:3]
	v_lshlrev_b32_e32 v4, 16, v13
	v_and_b32_e32 v5, 0xffff0000, v13
	v_pk_mul_f32 v[2:3], v[2:3], v[4:5]
	s_nop 0
	v_cvt_pk_bf16_f32 v9, v2, v3
	v_lshl_add_u64 v[2:3], s[2:3], 0, v[86:87]
	v_lshlrev_b64 v[2:3], 11, v[2:3]
	v_lshl_add_u64 v[2:3], v[94:95], 0, v[2:3]
	global_store_dwordx4 v[2:3], v[6:9], off
